# v15 plus K-loop LDS-DMA address simplification in P1 and P5: SGPR-base + 32-bit VGPR-offset form, no per-load 64-bit VALU add
# baseline (speedup 1.0000x reference)
; #define PG8_STAGE(bufoff, gbase, voff) do { _Pragma("unroll") for (int _i = 0; _i < 2; ++_i) \
;         __builtin_amdgcn_global_load_lds((const unsigned*)((const char*)(gbase) + (voff)[_i]), (PG8_LAS unsigned*)(lds + (bufoff) + ldsw + _i * 8192), 16, 0, 0); } while (0)
; #define PG8_LDA(dst, b, h) do { _Pragma("unroll") for (int m = 0; m < 4; ++m) _Pragma("unroll") for (int k = 0; k < 2; ++k) dst[m][k] = *(const PG8_LAS bf16x8*)(lds + PG8_SA(b, h) + aoff + m * 2048 + k * 1024); } while (0)
; #define PG8_LDB(dst, b, h) do { _Pragma("unroll") for (int n = 0; n < 2; ++n) _Pragma("unroll") for (int k = 0; k < 2; ++k) dst[n][k] = *(const PG8_LAS bf16x8*)(lds + PG8_SB(b, h) + boff + n * 2048 + k * 1024); } while (0)
; #define PG8_MMA(ai, bj, At, Bt) do { __builtin_amdgcn_s_setprio(1); _Pragma("unroll") for (int m = 0; m < 4; ++m) _Pragma("unroll") for (int n = 0; n < 2; ++n) _Pragma("unroll") for (int k = 0; k < 2; ++k) \
;         acc[ai][bj][m][n] = __builtin_amdgcn_mfma_f32_16x16x32_bf16(Bt[n][k], At[m][k], acc[ai][bj][m][n], 0, 0, 0); __builtin_amdgcn_s_setprio(0); } while (0)
; #define PG8_WAIT_V(n) asm volatile("s_waitcnt vmcnt(" #n ")" ::: "memory")
; #define PG8_WAIT_L(n) asm volatile("s_waitcnt lgkmcnt(" #n ")" ::: "memory")
; #define PG8_BAR __builtin_amdgcn_s_barrier()
; #define PG8_SCHED __builtin_amdgcn_sched_barrier(0)
; template <class Epi, class Sched, bool ALIGN_EPI = false, bool SP2 = false>
; __device__ __forceinline__ void gemm_phase(PG8_LAS unsigned char* lds, const Gemm g, const Sched& S, const Epi& E, const int wave_s) {
;     ...
;             PG8_LDB(B0, 0, 0); PG8_LDB(B1, 0, 1); PG8_SCHED; PG8_LDA(At, 0, 0); PG8_STAGE(PG8_SA(1, 1), a1 + hA, voffA);
;             PG8_WAIT_V(8); PG8_WAIT_L(0); PG8_BAR; PG8_MMA(0, 0, At, B0); PG8_MMA(0, 1, At, B1); PG8_BAR; PG8_SCHED;
;             PG8_LDA(At, 0, 1); PG8_STAGE(PG8_SB(0, 0), b2, voffB); PG8_STAGE(PG8_SB(0, 1), b2 + hB, voffB); PG8_STAGE(PG8_SA(0, 0), a2, voffA);
;             PG8_WAIT_V(8); PG8_WAIT_L(0); PG8_BAR; PG8_MMA(1, 0, At, B0); PG8_MMA(1, 1, At, B1); PG8_BAR; PG8_SCHED;
;             PG8_LDB(B0, 1, 0); PG8_LDB(B1, 1, 1); PG8_SCHED; PG8_LDA(At, 1, 0); PG8_STAGE(PG8_SA(0, 1), a2 + hA, voffA);
.LBB0_204:
	v_add_u32_e32 v126, s93, v185
	ds_read_b128 v[114:117], v126
	ds_read_b128 v[118:121], v126 offset:1024
	ds_read_b128 v[122:125], v126 offset:2048
	ds_read_b128 v[144:147], v126 offset:3072
	v_add_u32_e32 v126, s94, v185
	ds_read_b128 v[148:151], v126
	ds_read_b128 v[176:179], v126 offset:1024
	ds_read_b128 v[202:205], v126 offset:2048
	ds_read_b128 v[206:209], v126 offset:3072
	s_add_u32 s63, s6, 0xfffc0080
	s_addc_u32 s65, s7, -1
	s_and_b64 s[72:73], s[72:73], exec
	s_cselect_b32 s75, s5, s65
	s_cselect_b32 s74, s8, s63
	s_cselect_b32 s73, s9, s34
	s_cselect_b32 s72, s12, s13
	s_add_i32 m0, s71, 0xc000
	ds_read_b128 v[210:213], v189
	ds_read_b128 v[214:217], v189 offset:1024
	ds_read_b128 v[218:221], v189 offset:2048
	ds_read_b128 v[222:225], v189 offset:3072
	ds_read_b128 v[226:229], v189 offset:4096
	ds_read_b128 v[230:233], v189 offset:5120
	ds_read_b128 v[234:237], v189 offset:6144
	ds_read_b128 v[238:241], v189 offset:7168
	global_load_lds_dwordx4 v168, s[6:7]
	s_add_i32 m0, s71, 0xe000
	s_nop 0
	global_load_lds_dwordx4 v170, s[6:7]
	s_waitcnt vmcnt(8)
	s_waitcnt lgkmcnt(0)
	s_barrier
	s_setprio 1
	s_waitcnt lgkmcnt(0)
	v_mfma_f32_16x16x32_bf16 v[140:143], v[114:117], v[210:213], v[140:143]
	v_mfma_f32_16x16x32_bf16 v[136:139], v[122:125], v[210:213], v[136:139]
	v_mfma_f32_16x16x32_bf16 v[108:111], v[114:117], v[218:221], v[108:111]
	v_mfma_f32_16x16x32_bf16 v[104:107], v[122:125], v[218:221], v[104:107]
	v_mfma_f32_16x16x32_bf16 v[92:95], v[114:117], v[226:229], v[92:95]
	v_mfma_f32_16x16x32_bf16 v[88:91], v[122:125], v[226:229], v[88:91]
	v_mfma_f32_16x16x32_bf16 v[76:79], v[114:117], v[234:237], v[76:79]
	v_mfma_f32_16x16x32_bf16 v[72:75], v[122:125], v[234:237], v[72:75]
	v_mfma_f32_16x16x32_bf16 v[140:143], v[118:121], v[214:217], v[140:143]
	v_mfma_f32_16x16x32_bf16 v[136:139], v[144:147], v[214:217], v[136:139]
	v_mfma_f32_16x16x32_bf16 v[108:111], v[118:121], v[222:225], v[108:111]
	v_mfma_f32_16x16x32_bf16 v[104:107], v[144:147], v[222:225], v[104:107]
	v_mfma_f32_16x16x32_bf16 v[92:95], v[118:121], v[230:233], v[92:95]
	v_mfma_f32_16x16x32_bf16 v[88:91], v[144:147], v[230:233], v[88:91]
	v_mfma_f32_16x16x32_bf16 v[76:79], v[118:121], v[238:241], v[76:79]
	v_mfma_f32_16x16x32_bf16 v[72:75], v[144:147], v[238:241], v[72:75]
	s_setprio 0
	s_setprio 1
	v_mfma_f32_16x16x32_bf16 v[132:135], v[148:151], v[210:213], v[132:135]
	v_mfma_f32_16x16x32_bf16 v[126:129], v[202:205], v[210:213], v[128:131]
	v_mfma_f32_16x16x32_bf16 v[100:103], v[148:151], v[218:221], v[100:103]
	v_mfma_f32_16x16x32_bf16 v[96:99], v[202:205], v[218:221], v[96:99]
	v_mfma_f32_16x16x32_bf16 v[84:87], v[148:151], v[226:229], v[84:87]
	v_mfma_f32_16x16x32_bf16 v[80:83], v[202:205], v[226:229], v[80:83]
	v_mfma_f32_16x16x32_bf16 v[68:71], v[148:151], v[234:237], v[68:71]
	v_mfma_f32_16x16x32_bf16 v[64:67], v[202:205], v[234:237], v[64:67]
	v_mfma_f32_16x16x32_bf16 v[132:135], v[176:179], v[214:217], v[132:135]
	v_mfma_f32_16x16x32_bf16 v[126:129], v[206:209], v[214:217], v[126:129]
	v_mfma_f32_16x16x32_bf16 v[100:103], v[176:179], v[222:225], v[100:103]
	v_mfma_f32_16x16x32_bf16 v[96:99], v[206:209], v[222:225], v[96:99]
	v_mfma_f32_16x16x32_bf16 v[84:87], v[176:179], v[230:233], v[84:87]
	v_mfma_f32_16x16x32_bf16 v[80:83], v[206:209], v[230:233], v[80:83]
	v_mfma_f32_16x16x32_bf16 v[68:71], v[176:179], v[238:241], v[68:71]
	v_mfma_f32_16x16x32_bf16 v[64:67], v[206:209], v[238:241], v[64:67]
	s_setprio 0
	s_barrier
	s_add_i32 s63, s93, s31
	s_add_u32 s98, s72, 0x80
	s_addc_u32 s99, s73, 0
	s_mov_b32 m0, s63
	ds_read_b128 v[210:213], v189 offset:16384
	ds_read_b128 v[214:217], v189 offset:17408
	ds_read_b128 v[218:221], v189 offset:18432
	ds_read_b128 v[222:225], v189 offset:19456
	ds_read_b128 v[226:229], v189 offset:20480
	ds_read_b128 v[230:233], v189 offset:21504
	ds_read_b128 v[234:237], v189 offset:22528
	ds_read_b128 v[238:241], v189 offset:23552
	global_load_lds_dwordx4 v154, s[72:73]
	s_add_i32 m0, s63, 0x2000
	s_add_u32 s76, s72, 0x40000
	s_addc_u32 s77, s73, 0
	s_add_i32 s63, s94, s31
	global_load_lds_dwordx4 v158, s[72:73]
	s_mov_b32 m0, s63
	s_add_u32 s100, s74, 0x80
	s_addc_u32 s101, s75, 0
	global_load_lds_dwordx4 v154, s[76:77]
	s_add_i32 m0, s63, 0x2000
	s_nop 0
	global_load_lds_dwordx4 v158, s[76:77]
	s_mov_b32 m0, s71
	s_nop 0
	global_load_lds_dwordx4 v152, s[74:75]
	s_mov_b32 m0, s78
	s_nop 0
	global_load_lds_dwordx4 v156, s[74:75]
	s_waitcnt vmcnt(8)
	s_waitcnt lgkmcnt(0)
	s_barrier
	s_setprio 1
	s_waitcnt lgkmcnt(0)
	v_mfma_f32_16x16x32_bf16 v[60:63], v[114:117], v[210:213], v[60:63]
	v_mfma_f32_16x16x32_bf16 v[56:59], v[122:125], v[210:213], v[56:59]
	v_mfma_f32_16x16x32_bf16 v[44:47], v[114:117], v[218:221], v[44:47]
	v_mfma_f32_16x16x32_bf16 v[40:43], v[122:125], v[218:221], v[40:43]
	v_mfma_f32_16x16x32_bf16 v[28:31], v[114:117], v[226:229], v[28:31]
	v_mfma_f32_16x16x32_bf16 v[24:27], v[122:125], v[226:229], v[24:27]
	v_mfma_f32_16x16x32_bf16 v[12:15], v[114:117], v[234:237], v[12:15]
	v_mfma_f32_16x16x32_bf16 v[8:11], v[122:125], v[234:237], v[8:11]
	v_mfma_f32_16x16x32_bf16 v[60:63], v[118:121], v[214:217], v[60:63]
	v_mfma_f32_16x16x32_bf16 v[56:59], v[144:147], v[214:217], v[56:59]
	v_mfma_f32_16x16x32_bf16 v[44:47], v[118:121], v[222:225], v[44:47]
	v_mfma_f32_16x16x32_bf16 v[40:43], v[144:147], v[222:225], v[40:43]
	v_mfma_f32_16x16x32_bf16 v[28:31], v[118:121], v[230:233], v[28:31]
	v_mfma_f32_16x16x32_bf16 v[24:27], v[144:147], v[230:233], v[24:27]
	v_mfma_f32_16x16x32_bf16 v[12:15], v[118:121], v[238:241], v[12:15]
	v_mfma_f32_16x16x32_bf16 v[8:11], v[144:147], v[238:241], v[8:11]
	s_setprio 0
	s_setprio 1
	v_mfma_f32_16x16x32_bf16 v[52:55], v[148:151], v[210:213], v[52:55]
	v_mfma_f32_16x16x32_bf16 v[48:51], v[202:205], v[210:213], v[48:51]
	v_mfma_f32_16x16x32_bf16 v[36:39], v[148:151], v[218:221], v[36:39]
	v_mfma_f32_16x16x32_bf16 v[32:35], v[202:205], v[218:221], v[32:35]
	v_mfma_f32_16x16x32_bf16 v[20:23], v[148:151], v[226:229], v[20:23]
	v_mfma_f32_16x16x32_bf16 v[16:19], v[202:205], v[226:229], v[16:19]
	v_mfma_f32_16x16x32_bf16 v[4:7], v[148:151], v[234:237], v[4:7]
	v_mfma_f32_16x16x32_bf16 v[0:3], v[202:205], v[234:237], v[0:3]
	v_mfma_f32_16x16x32_bf16 v[52:55], v[176:179], v[214:217], v[52:55]
	v_mfma_f32_16x16x32_bf16 v[48:51], v[206:209], v[214:217], v[48:51]
	v_mfma_f32_16x16x32_bf16 v[36:39], v[176:179], v[222:225], v[36:39]
	v_mfma_f32_16x16x32_bf16 v[32:35], v[206:209], v[222:225], v[32:35]
	v_mfma_f32_16x16x32_bf16 v[20:23], v[176:179], v[230:233], v[20:23]
	v_mfma_f32_16x16x32_bf16 v[16:19], v[206:209], v[230:233], v[16:19]
	v_mfma_f32_16x16x32_bf16 v[4:7], v[176:179], v[238:241], v[4:7]
	v_mfma_f32_16x16x32_bf16 v[0:3], v[206:209], v[238:241], v[0:3]
	s_setprio 0
	s_barrier
; #define PG8_STAGE(bufoff, gbase, voff) do { _Pragma("unroll") for (int _i = 0; _i < 2; ++_i) \
;         __builtin_amdgcn_global_load_lds((const unsigned*)((const char*)(gbase) + (voff)[_i]), (PG8_LAS unsigned*)(lds + (bufoff) + ldsw + _i * 8192), 16, 0, 0); } while (0)
; #define PG8_LDA(dst, b, h) do { _Pragma("unroll") for (int m = 0; m < 4; ++m) _Pragma("unroll") for (int k = 0; k < 2; ++k) dst[m][k] = *(const PG8_LAS bf16x8*)(lds + PG8_SA(b, h) + aoff + m * 2048 + k * 1024); } while (0)
; #define PG8_LDB(dst, b, h) do { _Pragma("unroll") for (int n = 0; n < 2; ++n) _Pragma("unroll") for (int k = 0; k < 2; ++k) dst[n][k] = *(const PG8_LAS bf16x8*)(lds + PG8_SB(b, h) + boff + n * 2048 + k * 1024); } while (0)
; #define PG8_MMA(ai, bj, At, Bt) do { __builtin_amdgcn_s_setprio(1); _Pragma("unroll") for (int m = 0; m < 4; ++m) _Pragma("unroll") for (int n = 0; n < 2; ++n) _Pragma("unroll") for (int k = 0; k < 2; ++k) \
;         acc[ai][bj][m][n] = __builtin_amdgcn_mfma_f32_16x16x32_bf16(Bt[n][k], At[m][k], acc[ai][bj][m][n], 0, 0, 0); __builtin_amdgcn_s_setprio(0); } while (0)
; #define PG8_WAIT_V(n) asm volatile("s_waitcnt vmcnt(" #n ")" ::: "memory")
; #define PG8_WAIT_L(n) asm volatile("s_waitcnt lgkmcnt(" #n ")" ::: "memory")
; #define PG8_BAR __builtin_amdgcn_s_barrier()
; #define PG8_SCHED __builtin_amdgcn_sched_barrier(0)
; template <class Epi, class Sched, bool ALIGN_EPI = false, bool SP2 = false>
; __device__ __forceinline__ void gemm_phase(PG8_LAS unsigned char* lds, const Gemm g, const Sched& S, const Epi& E, const int wave_s) {
;     ...
;         for (int t = 0; t < nt; t += 2) {
;     ...
;             PG8_LDB(B0, 1, 0); PG8_LDB(B1, 1, 1); PG8_SCHED; PG8_LDA(At, 1, 0); PG8_STAGE(PG8_SA(0, 1), a2 + hA, voffA);
;             PG8_WAIT_V(8); PG8_WAIT_L(0); PG8_BAR; PG8_MMA(0, 0, At, B0); PG8_MMA(0, 1, At, B1); PG8_BAR; PG8_SCHED;
;             PG8_LDA(At, 1, 1); PG8_STAGE(PG8_SB(1, 0), b3, voffB); PG8_STAGE(PG8_SB(1, 1), b3 + hB, voffB); PG8_STAGE(PG8_SA(1, 0), a3, voffA);
;             PG8_WAIT_V(8); PG8_WAIT_L(0); PG8_BAR; PG8_MMA(1, 0, At, B0); PG8_MMA(1, 1, At, B1); PG8_BAR; PG8_SCHED;
	s_add_i32 s63, 0, 0x18000
	v_add_u32_e32 v130, s63, v185
	s_add_i32 s65, 0, 0x1c000
	ds_read_b128 v[114:117], v130
	ds_read_b128 v[118:121], v130 offset:1024
	ds_read_b128 v[122:125], v130 offset:2048
	ds_read_b128 v[144:147], v130 offset:3072
	v_add_u32_e32 v130, s65, v185
	ds_read_b128 v[148:151], v130
	ds_read_b128 v[176:179], v130 offset:1024
	ds_read_b128 v[202:205], v130 offset:2048
	ds_read_b128 v[206:209], v130 offset:3072
	s_add_u32 s74, s74, 0x40000
	s_addc_u32 s75, s75, 0
	s_mov_b32 m0, s79
	ds_read_b128 v[210:213], v189 offset:32768
	ds_read_b128 v[214:217], v189 offset:33792
	ds_read_b128 v[218:221], v189 offset:34816
	ds_read_b128 v[222:225], v189 offset:35840
	ds_read_b128 v[226:229], v189 offset:36864
	ds_read_b128 v[230:233], v189 offset:37888
	ds_read_b128 v[234:237], v189 offset:38912
	ds_read_b128 v[238:241], v189 offset:39936
	global_load_lds_dwordx4 v152, s[74:75]
	s_mov_b32 m0, s80
	s_nop 0
	global_load_lds_dwordx4 v156, s[74:75]
	s_waitcnt vmcnt(8)
	s_waitcnt lgkmcnt(0)
	s_barrier
	s_setprio 1
	s_waitcnt lgkmcnt(0)
	v_mfma_f32_16x16x32_bf16 v[140:143], v[114:117], v[210:213], v[140:143]
	v_mfma_f32_16x16x32_bf16 v[136:139], v[122:125], v[210:213], v[136:139]
	v_mfma_f32_16x16x32_bf16 v[108:111], v[114:117], v[218:221], v[108:111]
	v_mfma_f32_16x16x32_bf16 v[104:107], v[122:125], v[218:221], v[104:107]
	v_mfma_f32_16x16x32_bf16 v[92:95], v[114:117], v[226:229], v[92:95]
	v_mfma_f32_16x16x32_bf16 v[88:91], v[122:125], v[226:229], v[88:91]
	v_mfma_f32_16x16x32_bf16 v[76:79], v[114:117], v[234:237], v[76:79]
	v_mfma_f32_16x16x32_bf16 v[72:75], v[122:125], v[234:237], v[72:75]
	v_mfma_f32_16x16x32_bf16 v[140:143], v[118:121], v[214:217], v[140:143]
	v_mfma_f32_16x16x32_bf16 v[136:139], v[144:147], v[214:217], v[136:139]
	v_mfma_f32_16x16x32_bf16 v[108:111], v[118:121], v[222:225], v[108:111]
	v_mfma_f32_16x16x32_bf16 v[104:107], v[144:147], v[222:225], v[104:107]
	v_mfma_f32_16x16x32_bf16 v[92:95], v[118:121], v[230:233], v[92:95]
	v_mfma_f32_16x16x32_bf16 v[88:91], v[144:147], v[230:233], v[88:91]
	v_mfma_f32_16x16x32_bf16 v[76:79], v[118:121], v[238:241], v[76:79]
	v_mfma_f32_16x16x32_bf16 v[72:75], v[144:147], v[238:241], v[72:75]
	s_setprio 0
	s_setprio 1
	v_mfma_f32_16x16x32_bf16 v[130:133], v[148:151], v[210:213], v[132:135]
	v_mfma_f32_16x16x32_bf16 v[126:129], v[202:205], v[210:213], v[126:129]
	v_mfma_f32_16x16x32_bf16 v[100:103], v[148:151], v[218:221], v[100:103]
	v_mfma_f32_16x16x32_bf16 v[96:99], v[202:205], v[218:221], v[96:99]
	v_mfma_f32_16x16x32_bf16 v[84:87], v[148:151], v[226:229], v[84:87]
	v_mfma_f32_16x16x32_bf16 v[80:83], v[202:205], v[226:229], v[80:83]
	v_mfma_f32_16x16x32_bf16 v[68:71], v[148:151], v[234:237], v[68:71]
	v_mfma_f32_16x16x32_bf16 v[64:67], v[202:205], v[234:237], v[64:67]
	v_mfma_f32_16x16x32_bf16 v[132:135], v[176:179], v[214:217], v[130:133]
	v_mfma_f32_16x16x32_bf16 v[128:131], v[206:209], v[214:217], v[126:129]
	v_mfma_f32_16x16x32_bf16 v[100:103], v[176:179], v[222:225], v[100:103]
	v_mfma_f32_16x16x32_bf16 v[96:99], v[206:209], v[222:225], v[96:99]
	v_mfma_f32_16x16x32_bf16 v[84:87], v[176:179], v[230:233], v[84:87]
	v_mfma_f32_16x16x32_bf16 v[80:83], v[206:209], v[230:233], v[80:83]
	v_mfma_f32_16x16x32_bf16 v[68:71], v[176:179], v[238:241], v[68:71]
	v_mfma_f32_16x16x32_bf16 v[64:67], v[206:209], v[238:241], v[64:67]
	s_setprio 0
	s_barrier
	s_add_i32 s63, s63, s31
	s_mov_b32 m0, s63
	ds_read_b128 v[210:213], v189 offset:49152
	ds_read_b128 v[214:217], v189 offset:50176
	ds_read_b128 v[218:221], v189 offset:51200
	ds_read_b128 v[222:225], v189 offset:52224
	ds_read_b128 v[226:229], v189 offset:53248
	ds_read_b128 v[230:233], v189 offset:54272
	ds_read_b128 v[234:237], v189 offset:55296
	ds_read_b128 v[238:241], v189 offset:56320
	global_load_lds_dwordx4 v154, s[98:99]
	s_add_i32 m0, s63, 0x2000
	s_add_u32 s72, s72, 0x40080
	s_addc_u32 s73, s73, 0
	s_add_i32 s63, s65, s31
	global_load_lds_dwordx4 v158, s[98:99]
	s_mov_b32 m0, s63
	s_nop 0
	global_load_lds_dwordx4 v154, s[72:73]
	s_add_i32 m0, s63, 0x2000
	s_nop 0
	global_load_lds_dwordx4 v158, s[72:73]
	s_mov_b32 m0, s83
	s_nop 0
	global_load_lds_dwordx4 v152, s[100:101]
	s_mov_b32 m0, s88
	s_nop 0
	global_load_lds_dwordx4 v156, s[100:101]
	s_waitcnt vmcnt(8)
	s_waitcnt lgkmcnt(0)
	s_barrier
	s_setprio 1
	s_waitcnt lgkmcnt(0)
	v_mfma_f32_16x16x32_bf16 v[60:63], v[114:117], v[210:213], v[60:63]
	v_mfma_f32_16x16x32_bf16 v[56:59], v[122:125], v[210:213], v[56:59]
	v_mfma_f32_16x16x32_bf16 v[44:47], v[114:117], v[218:221], v[44:47]
	v_mfma_f32_16x16x32_bf16 v[40:43], v[122:125], v[218:221], v[40:43]
	v_mfma_f32_16x16x32_bf16 v[28:31], v[114:117], v[226:229], v[28:31]
	v_mfma_f32_16x16x32_bf16 v[24:27], v[122:125], v[226:229], v[24:27]
	v_mfma_f32_16x16x32_bf16 v[12:15], v[114:117], v[234:237], v[12:15]
	v_mfma_f32_16x16x32_bf16 v[8:11], v[122:125], v[234:237], v[8:11]
	v_mfma_f32_16x16x32_bf16 v[60:63], v[118:121], v[214:217], v[60:63]
	v_mfma_f32_16x16x32_bf16 v[56:59], v[144:147], v[214:217], v[56:59]
	v_mfma_f32_16x16x32_bf16 v[44:47], v[118:121], v[222:225], v[44:47]
	v_mfma_f32_16x16x32_bf16 v[40:43], v[144:147], v[222:225], v[40:43]
	v_mfma_f32_16x16x32_bf16 v[28:31], v[118:121], v[230:233], v[28:31]
	v_mfma_f32_16x16x32_bf16 v[24:27], v[144:147], v[230:233], v[24:27]
	v_mfma_f32_16x16x32_bf16 v[12:15], v[118:121], v[238:241], v[12:15]
	v_mfma_f32_16x16x32_bf16 v[8:11], v[144:147], v[238:241], v[8:11]
	s_setprio 0
	s_setprio 1
	v_mfma_f32_16x16x32_bf16 v[52:55], v[148:151], v[210:213], v[52:55]
	v_mfma_f32_16x16x32_bf16 v[48:51], v[202:205], v[210:213], v[48:51]
	v_mfma_f32_16x16x32_bf16 v[36:39], v[148:151], v[218:221], v[36:39]
	v_mfma_f32_16x16x32_bf16 v[32:35], v[202:205], v[218:221], v[32:35]
	v_mfma_f32_16x16x32_bf16 v[20:23], v[148:151], v[226:229], v[20:23]
	v_mfma_f32_16x16x32_bf16 v[16:19], v[202:205], v[226:229], v[16:19]
	v_mfma_f32_16x16x32_bf16 v[4:7], v[148:151], v[234:237], v[4:7]
	v_mfma_f32_16x16x32_bf16 v[0:3], v[202:205], v[234:237], v[0:3]
	v_mfma_f32_16x16x32_bf16 v[52:55], v[176:179], v[214:217], v[52:55]
	v_mfma_f32_16x16x32_bf16 v[48:51], v[206:209], v[214:217], v[48:51]
	v_mfma_f32_16x16x32_bf16 v[36:39], v[176:179], v[222:225], v[36:39]
	v_mfma_f32_16x16x32_bf16 v[32:35], v[206:209], v[222:225], v[32:35]
	v_mfma_f32_16x16x32_bf16 v[20:23], v[176:179], v[230:233], v[20:23]
	v_mfma_f32_16x16x32_bf16 v[16:19], v[206:209], v[230:233], v[16:19]
	v_mfma_f32_16x16x32_bf16 v[4:7], v[176:179], v[238:241], v[4:7]
	v_mfma_f32_16x16x32_bf16 v[0:3], v[206:209], v[238:241], v[0:3]
	s_setprio 0
	s_barrier
	s_add_i32 s35, s35, 2
	s_add_u32 s6, s6, 0x100
	s_addc_u32 s7, s7, 0
	s_add_u32 s13, s13, 0x100
	s_addc_u32 s34, s34, 0
	s_cmp_gt_u32 s35, 13
	s_cbranch_scc1 .LBB0_207

; #define PG8_STAGE(bufoff, gbase, voff) do { _Pragma("unroll") for (int _i = 0; _i < 2; ++_i) \
;         __builtin_amdgcn_global_load_lds((const unsigned*)((const char*)(gbase) + (voff)[_i]), (PG8_LAS unsigned*)(lds + (bufoff) + ldsw + _i * 8192), 16, 0, 0); } while (0)
; #define PG8_LDA(dst, b, h) do { _Pragma("unroll") for (int m = 0; m < 4; ++m) _Pragma("unroll") for (int k = 0; k < 2; ++k) dst[m][k] = *(const PG8_LAS bf16x8*)(lds + PG8_SA(b, h) + aoff + m * 2048 + k * 1024); } while (0)
; #define PG8_LDB(dst, b, h) do { _Pragma("unroll") for (int n = 0; n < 2; ++n) _Pragma("unroll") for (int k = 0; k < 2; ++k) dst[n][k] = *(const PG8_LAS bf16x8*)(lds + PG8_SB(b, h) + boff + n * 2048 + k * 1024); } while (0)
; #define PG8_MMA(ai, bj, At, Bt) do { __builtin_amdgcn_s_setprio(1); _Pragma("unroll") for (int m = 0; m < 4; ++m) _Pragma("unroll") for (int n = 0; n < 2; ++n) _Pragma("unroll") for (int k = 0; k < 2; ++k) \
;         acc[ai][bj][m][n] = __builtin_amdgcn_mfma_f32_16x16x32_bf16(Bt[n][k], At[m][k], acc[ai][bj][m][n], 0, 0, 0); __builtin_amdgcn_s_setprio(0); } while (0)
; #define PG8_WAIT_V(n) asm volatile("s_waitcnt vmcnt(" #n ")" ::: "memory")
; #define PG8_WAIT_L(n) asm volatile("s_waitcnt lgkmcnt(" #n ")" ::: "memory")
; #define PG8_BAR __builtin_amdgcn_s_barrier()
; #define PG8_SCHED __builtin_amdgcn_sched_barrier(0)
; template <class Epi, class Sched, bool ALIGN_EPI = false, bool SP2 = false>
; __device__ __forceinline__ void gemm_phase(PG8_LAS unsigned char* lds, const Gemm g, const Sched& S, const Epi& E, const int wave_s) {
;     ...
;             PG8_LDB(B0, 0, 0); PG8_LDB(B1, 0, 1); PG8_SCHED; PG8_LDA(At, 0, 0); PG8_STAGE(PG8_SA(1, 1), a1 + hA, voffA);
;             PG8_WAIT_V(8); PG8_WAIT_L(0); PG8_BAR; PG8_MMA(0, 0, At, B0); PG8_MMA(0, 1, At, B1); PG8_BAR; PG8_SCHED;
;             PG8_LDA(At, 0, 1); PG8_STAGE(PG8_SB(0, 0), b2, voffB); PG8_STAGE(PG8_SB(0, 1), b2 + hB, voffB); PG8_STAGE(PG8_SA(0, 0), a2, voffA);
;             PG8_WAIT_V(8); PG8_WAIT_L(0); PG8_BAR; PG8_MMA(1, 0, At, B0); PG8_MMA(1, 1, At, B1); PG8_BAR; PG8_SCHED;
;             PG8_LDB(B0, 1, 0); PG8_LDB(B1, 1, 1); PG8_SCHED; PG8_LDA(At, 1, 0); PG8_STAGE(PG8_SA(0, 1), a2 + hA, voffA);
.LBB0_782:
	v_add_u32_e32 v161, s66, v149
	ds_read_b128 v[162:165], v161
	ds_read_b128 v[166:169], v161 offset:1024
	ds_read_b128 v[170:173], v161 offset:2048
	ds_read_b128 v[174:177], v161 offset:3072
	v_add_u32_e32 v161, s67, v149
	ds_read_b128 v[178:181], v161
	ds_read_b128 v[182:185], v161 offset:1024
	ds_read_b128 v[186:189], v161 offset:2048
	ds_read_b128 v[190:193], v161 offset:3072
	s_add_u32 s58, s50, 0xfffc0080
	s_addc_u32 s59, s51, -1
	s_and_b64 s[56:57], s[56:57], exec
	s_cselect_b32 s59, s9, s59
	s_cselect_b32 s58, s45, s58
	s_cselect_b32 s57, s43, s74
	s_cselect_b32 s56, s72, s73
	s_add_i32 m0, s34, 0xc000
	ds_read_b128 v[194:197], v151
	ds_read_b128 v[198:201], v151 offset:1024
	ds_read_b128 v[202:205], v151 offset:2048
	ds_read_b128 v[206:209], v151 offset:3072
	ds_read_b128 v[210:213], v151 offset:4096
	ds_read_b128 v[218:221], v151 offset:5120
	ds_read_b128 v[222:225], v151 offset:6144
	ds_read_b128 v[226:229], v151 offset:7168
	global_load_lds_dwordx4 v136, s[50:51]
	s_add_i32 m0, s34, 0xe000
	s_nop 0
	global_load_lds_dwordx4 v138, s[50:51]
	s_waitcnt vmcnt(8)
	s_waitcnt lgkmcnt(0)
	s_barrier
	s_setprio 1
	s_waitcnt lgkmcnt(0)
	v_mfma_f32_16x16x32_bf16 v[124:127], v[162:165], v[194:197], v[124:127]
	v_mfma_f32_16x16x32_bf16 v[120:123], v[170:173], v[194:197], v[120:123]
	v_mfma_f32_16x16x32_bf16 v[108:111], v[162:165], v[202:205], v[108:111]
	v_mfma_f32_16x16x32_bf16 v[104:107], v[170:173], v[202:205], v[104:107]
	v_mfma_f32_16x16x32_bf16 v[92:95], v[162:165], v[210:213], v[92:95]
	v_mfma_f32_16x16x32_bf16 v[88:91], v[170:173], v[210:213], v[88:91]
	v_mfma_f32_16x16x32_bf16 v[76:79], v[162:165], v[222:225], v[76:79]
	v_mfma_f32_16x16x32_bf16 v[72:75], v[170:173], v[222:225], v[72:75]
	v_mfma_f32_16x16x32_bf16 v[124:127], v[166:169], v[198:201], v[124:127]
	v_mfma_f32_16x16x32_bf16 v[120:123], v[174:177], v[198:201], v[120:123]
	v_mfma_f32_16x16x32_bf16 v[108:111], v[166:169], v[206:209], v[108:111]
	v_mfma_f32_16x16x32_bf16 v[104:107], v[174:177], v[206:209], v[104:107]
	v_mfma_f32_16x16x32_bf16 v[92:95], v[166:169], v[218:221], v[92:95]
	v_mfma_f32_16x16x32_bf16 v[88:91], v[174:177], v[218:221], v[88:91]
	v_mfma_f32_16x16x32_bf16 v[76:79], v[166:169], v[226:229], v[76:79]
	v_mfma_f32_16x16x32_bf16 v[72:75], v[174:177], v[226:229], v[72:75]
	s_setprio 0
	s_setprio 1
	v_mfma_f32_16x16x32_bf16 v[116:119], v[178:181], v[194:197], v[116:119]
	v_mfma_f32_16x16x32_bf16 v[112:115], v[186:189], v[194:197], v[112:115]
	v_mfma_f32_16x16x32_bf16 v[100:103], v[178:181], v[202:205], v[100:103]
	v_mfma_f32_16x16x32_bf16 v[96:99], v[186:189], v[202:205], v[96:99]
	v_mfma_f32_16x16x32_bf16 v[84:87], v[178:181], v[210:213], v[84:87]
	v_mfma_f32_16x16x32_bf16 v[80:83], v[186:189], v[210:213], v[80:83]
	v_mfma_f32_16x16x32_bf16 v[68:71], v[178:181], v[222:225], v[68:71]
	v_mfma_f32_16x16x32_bf16 v[64:67], v[186:189], v[222:225], v[64:67]
	v_mfma_f32_16x16x32_bf16 v[116:119], v[182:185], v[198:201], v[116:119]
	v_mfma_f32_16x16x32_bf16 v[112:115], v[190:193], v[198:201], v[112:115]
	v_mfma_f32_16x16x32_bf16 v[100:103], v[182:185], v[206:209], v[100:103]
	v_mfma_f32_16x16x32_bf16 v[96:99], v[190:193], v[206:209], v[96:99]
	v_mfma_f32_16x16x32_bf16 v[84:87], v[182:185], v[218:221], v[84:87]
	v_mfma_f32_16x16x32_bf16 v[80:83], v[190:193], v[218:221], v[80:83]
	v_mfma_f32_16x16x32_bf16 v[68:71], v[182:185], v[226:229], v[68:71]
	v_mfma_f32_16x16x32_bf16 v[64:67], v[190:193], v[226:229], v[64:67]
	s_setprio 0
	s_barrier
	s_add_i32 s76, s66, s11
	s_add_u32 s98, s56, 0x80
	s_addc_u32 s99, s57, 0
	s_mov_b32 m0, s76
	ds_read_b128 v[194:197], v151 offset:16384
	ds_read_b128 v[198:201], v151 offset:17408
	ds_read_b128 v[202:205], v151 offset:18432
	ds_read_b128 v[206:209], v151 offset:19456
	ds_read_b128 v[210:213], v151 offset:20480
	ds_read_b128 v[218:221], v151 offset:21504
	ds_read_b128 v[222:225], v151 offset:22528
	ds_read_b128 v[226:229], v151 offset:23552
	global_load_lds_dwordx4 v132, s[56:57]
	s_add_i32 m0, s76, 0x2000
	s_add_u32 s76, s56, 0x40000
	s_addc_u32 s77, s57, 0
	s_add_i32 s78, s67, s11
	global_load_lds_dwordx4 v128, s[56:57]
	s_mov_b32 m0, s78
	s_add_u32 s100, s58, 0x80
	s_addc_u32 s101, s59, 0
	global_load_lds_dwordx4 v132, s[76:77]
	s_add_i32 m0, s78, 0x2000
	s_nop 0
	global_load_lds_dwordx4 v128, s[76:77]
	s_mov_b32 m0, s34
	s_nop 0
	global_load_lds_dwordx4 v134, s[58:59]
	s_mov_b32 m0, s35
	s_nop 0
	global_load_lds_dwordx4 v130, s[58:59]
	s_waitcnt vmcnt(8)
	s_waitcnt lgkmcnt(0)
	s_barrier
	s_setprio 1
	s_waitcnt lgkmcnt(0)
	v_mfma_f32_16x16x32_bf16 v[60:63], v[162:165], v[194:197], v[60:63]
	v_mfma_f32_16x16x32_bf16 v[56:59], v[170:173], v[194:197], v[56:59]
	v_mfma_f32_16x16x32_bf16 v[44:47], v[162:165], v[202:205], v[44:47]
	v_mfma_f32_16x16x32_bf16 v[40:43], v[170:173], v[202:205], v[40:43]
	v_mfma_f32_16x16x32_bf16 v[28:31], v[162:165], v[210:213], v[28:31]
	v_mfma_f32_16x16x32_bf16 v[24:27], v[170:173], v[210:213], v[24:27]
	v_mfma_f32_16x16x32_bf16 v[12:15], v[162:165], v[222:225], v[12:15]
	v_mfma_f32_16x16x32_bf16 v[8:11], v[170:173], v[222:225], v[8:11]
	v_mfma_f32_16x16x32_bf16 v[60:63], v[166:169], v[198:201], v[60:63]
	v_mfma_f32_16x16x32_bf16 v[56:59], v[174:177], v[198:201], v[56:59]
	v_mfma_f32_16x16x32_bf16 v[44:47], v[166:169], v[206:209], v[44:47]
	v_mfma_f32_16x16x32_bf16 v[40:43], v[174:177], v[206:209], v[40:43]
	v_mfma_f32_16x16x32_bf16 v[28:31], v[166:169], v[218:221], v[28:31]
	v_mfma_f32_16x16x32_bf16 v[24:27], v[174:177], v[218:221], v[24:27]
	v_mfma_f32_16x16x32_bf16 v[12:15], v[166:169], v[226:229], v[12:15]
	v_mfma_f32_16x16x32_bf16 v[8:11], v[174:177], v[226:229], v[8:11]
	s_setprio 0
	s_setprio 1
	v_mfma_f32_16x16x32_bf16 v[52:55], v[178:181], v[194:197], v[52:55]
	v_mfma_f32_16x16x32_bf16 v[48:51], v[186:189], v[194:197], v[48:51]
	v_mfma_f32_16x16x32_bf16 v[36:39], v[178:181], v[202:205], v[36:39]
	v_mfma_f32_16x16x32_bf16 v[32:35], v[186:189], v[202:205], v[32:35]
	v_mfma_f32_16x16x32_bf16 v[20:23], v[178:181], v[210:213], v[20:23]
	v_mfma_f32_16x16x32_bf16 v[16:19], v[186:189], v[210:213], v[16:19]
	v_mfma_f32_16x16x32_bf16 v[4:7], v[178:181], v[222:225], v[4:7]
	v_mfma_f32_16x16x32_bf16 v[0:3], v[186:189], v[222:225], v[0:3]
	v_mfma_f32_16x16x32_bf16 v[52:55], v[182:185], v[198:201], v[52:55]
	v_mfma_f32_16x16x32_bf16 v[48:51], v[190:193], v[198:201], v[48:51]
	v_mfma_f32_16x16x32_bf16 v[36:39], v[182:185], v[206:209], v[36:39]
	v_mfma_f32_16x16x32_bf16 v[32:35], v[190:193], v[206:209], v[32:35]
	v_mfma_f32_16x16x32_bf16 v[20:23], v[182:185], v[218:221], v[20:23]
	v_mfma_f32_16x16x32_bf16 v[16:19], v[190:193], v[218:221], v[16:19]
	v_mfma_f32_16x16x32_bf16 v[4:7], v[182:185], v[226:229], v[4:7]
	v_mfma_f32_16x16x32_bf16 v[0:3], v[190:193], v[226:229], v[0:3]
	s_setprio 0
	s_barrier
; #define PG8_STAGE(bufoff, gbase, voff) do { _Pragma("unroll") for (int _i = 0; _i < 2; ++_i) \
;         __builtin_amdgcn_global_load_lds((const unsigned*)((const char*)(gbase) + (voff)[_i]), (PG8_LAS unsigned*)(lds + (bufoff) + ldsw + _i * 8192), 16, 0, 0); } while (0)
; #define PG8_LDA(dst, b, h) do { _Pragma("unroll") for (int m = 0; m < 4; ++m) _Pragma("unroll") for (int k = 0; k < 2; ++k) dst[m][k] = *(const PG8_LAS bf16x8*)(lds + PG8_SA(b, h) + aoff + m * 2048 + k * 1024); } while (0)
; #define PG8_LDB(dst, b, h) do { _Pragma("unroll") for (int n = 0; n < 2; ++n) _Pragma("unroll") for (int k = 0; k < 2; ++k) dst[n][k] = *(const PG8_LAS bf16x8*)(lds + PG8_SB(b, h) + boff + n * 2048 + k * 1024); } while (0)
; #define PG8_MMA(ai, bj, At, Bt) do { __builtin_amdgcn_s_setprio(1); _Pragma("unroll") for (int m = 0; m < 4; ++m) _Pragma("unroll") for (int n = 0; n < 2; ++n) _Pragma("unroll") for (int k = 0; k < 2; ++k) \
;         acc[ai][bj][m][n] = __builtin_amdgcn_mfma_f32_16x16x32_bf16(Bt[n][k], At[m][k], acc[ai][bj][m][n], 0, 0, 0); __builtin_amdgcn_s_setprio(0); } while (0)
; #define PG8_WAIT_V(n) asm volatile("s_waitcnt vmcnt(" #n ")" ::: "memory")
; #define PG8_WAIT_L(n) asm volatile("s_waitcnt lgkmcnt(" #n ")" ::: "memory")
; #define PG8_BAR __builtin_amdgcn_s_barrier()
; #define PG8_SCHED __builtin_amdgcn_sched_barrier(0)
; template <class Epi, class Sched, bool ALIGN_EPI = false, bool SP2 = false>
; __device__ __forceinline__ void gemm_phase(PG8_LAS unsigned char* lds, const Gemm g, const Sched& S, const Epi& E, const int wave_s) {
;     ...
;             PG8_LDB(B0, 1, 0); PG8_LDB(B1, 1, 1); PG8_SCHED; PG8_LDA(At, 1, 0); PG8_STAGE(PG8_SA(0, 1), a2 + hA, voffA);
;             PG8_WAIT_V(8); PG8_WAIT_L(0); PG8_BAR; PG8_MMA(0, 0, At, B0); PG8_MMA(0, 1, At, B1); PG8_BAR; PG8_SCHED;
;             PG8_LDA(At, 1, 1); PG8_STAGE(PG8_SB(1, 0), b3, voffB); PG8_STAGE(PG8_SB(1, 1), b3 + hB, voffB); PG8_STAGE(PG8_SA(1, 0), a3, voffA);
;             PG8_WAIT_V(8); PG8_WAIT_L(0); PG8_BAR; PG8_MMA(1, 0, At, B0); PG8_MMA(1, 1, At, B1); PG8_BAR; PG8_SCHED;
	s_add_i32 s76, 0, 0x18000
	v_add_u32_e32 v161, s76, v149
	s_add_i32 s77, 0, 0x1c000
	ds_read_b128 v[162:165], v161
	ds_read_b128 v[166:169], v161 offset:1024
	ds_read_b128 v[170:173], v161 offset:2048
	ds_read_b128 v[174:177], v161 offset:3072
	v_add_u32_e32 v161, s77, v149
	ds_read_b128 v[178:181], v161
	ds_read_b128 v[182:185], v161 offset:1024
	ds_read_b128 v[186:189], v161 offset:2048
	ds_read_b128 v[190:193], v161 offset:3072
	s_add_u32 s58, s58, 0x40000
	s_addc_u32 s59, s59, 0
	s_mov_b32 m0, s60
	ds_read_b128 v[194:197], v151 offset:32768
	ds_read_b128 v[198:201], v151 offset:33792
	ds_read_b128 v[202:205], v151 offset:34816
	ds_read_b128 v[206:209], v151 offset:35840
	ds_read_b128 v[210:213], v151 offset:36864
	ds_read_b128 v[218:221], v151 offset:37888
	ds_read_b128 v[222:225], v151 offset:38912
	ds_read_b128 v[226:229], v151 offset:39936
	global_load_lds_dwordx4 v134, s[58:59]
	s_mov_b32 m0, s61
	s_nop 0
	global_load_lds_dwordx4 v130, s[58:59]
	s_waitcnt vmcnt(8)
	s_waitcnt lgkmcnt(0)
	s_barrier
	s_setprio 1
	s_waitcnt lgkmcnt(0)
	v_mfma_f32_16x16x32_bf16 v[124:127], v[162:165], v[194:197], v[124:127]
	v_mfma_f32_16x16x32_bf16 v[120:123], v[170:173], v[194:197], v[120:123]
	v_mfma_f32_16x16x32_bf16 v[108:111], v[162:165], v[202:205], v[108:111]
	v_mfma_f32_16x16x32_bf16 v[104:107], v[170:173], v[202:205], v[104:107]
	v_mfma_f32_16x16x32_bf16 v[92:95], v[162:165], v[210:213], v[92:95]
	v_mfma_f32_16x16x32_bf16 v[88:91], v[170:173], v[210:213], v[88:91]
	v_mfma_f32_16x16x32_bf16 v[76:79], v[162:165], v[222:225], v[76:79]
	v_mfma_f32_16x16x32_bf16 v[72:75], v[170:173], v[222:225], v[72:75]
	v_mfma_f32_16x16x32_bf16 v[124:127], v[166:169], v[198:201], v[124:127]
	v_mfma_f32_16x16x32_bf16 v[120:123], v[174:177], v[198:201], v[120:123]
	v_mfma_f32_16x16x32_bf16 v[108:111], v[166:169], v[206:209], v[108:111]
	v_mfma_f32_16x16x32_bf16 v[104:107], v[174:177], v[206:209], v[104:107]
	v_mfma_f32_16x16x32_bf16 v[92:95], v[166:169], v[218:221], v[92:95]
	v_mfma_f32_16x16x32_bf16 v[88:91], v[174:177], v[218:221], v[88:91]
	v_mfma_f32_16x16x32_bf16 v[76:79], v[166:169], v[226:229], v[76:79]
	v_mfma_f32_16x16x32_bf16 v[72:75], v[174:177], v[226:229], v[72:75]
	s_setprio 0
	s_setprio 1
	v_mfma_f32_16x16x32_bf16 v[116:119], v[178:181], v[194:197], v[116:119]
	v_mfma_f32_16x16x32_bf16 v[112:115], v[186:189], v[194:197], v[112:115]
	v_mfma_f32_16x16x32_bf16 v[100:103], v[178:181], v[202:205], v[100:103]
	v_mfma_f32_16x16x32_bf16 v[96:99], v[186:189], v[202:205], v[96:99]
	v_mfma_f32_16x16x32_bf16 v[84:87], v[178:181], v[210:213], v[84:87]
	v_mfma_f32_16x16x32_bf16 v[80:83], v[186:189], v[210:213], v[80:83]
	v_mfma_f32_16x16x32_bf16 v[68:71], v[178:181], v[222:225], v[68:71]
	v_mfma_f32_16x16x32_bf16 v[64:67], v[186:189], v[222:225], v[64:67]
	v_mfma_f32_16x16x32_bf16 v[116:119], v[182:185], v[198:201], v[116:119]
	v_mfma_f32_16x16x32_bf16 v[112:115], v[190:193], v[198:201], v[112:115]
	v_mfma_f32_16x16x32_bf16 v[100:103], v[182:185], v[206:209], v[100:103]
	v_mfma_f32_16x16x32_bf16 v[96:99], v[190:193], v[206:209], v[96:99]
	v_mfma_f32_16x16x32_bf16 v[84:87], v[182:185], v[218:221], v[84:87]
	v_mfma_f32_16x16x32_bf16 v[80:83], v[190:193], v[218:221], v[80:83]
	v_mfma_f32_16x16x32_bf16 v[68:71], v[182:185], v[226:229], v[68:71]
	v_mfma_f32_16x16x32_bf16 v[64:67], v[190:193], v[226:229], v[64:67]
	s_setprio 0
	s_barrier
	s_add_i32 s58, s76, s11
	s_mov_b32 m0, s58
	ds_read_b128 v[194:197], v151 offset:49152
	ds_read_b128 v[198:201], v151 offset:50176
	ds_read_b128 v[202:205], v151 offset:51200
	ds_read_b128 v[206:209], v151 offset:52224
	ds_read_b128 v[210:213], v151 offset:53248
	ds_read_b128 v[218:221], v151 offset:54272
	ds_read_b128 v[222:225], v151 offset:55296
	ds_read_b128 v[226:229], v151 offset:56320
	global_load_lds_dwordx4 v132, s[98:99]
	s_add_i32 m0, s58, 0x2000
	s_add_u32 s56, s56, 0x40080
	s_addc_u32 s57, s57, 0
	s_add_i32 s58, s77, s11
	global_load_lds_dwordx4 v128, s[98:99]
	s_mov_b32 m0, s58
	s_nop 0
	global_load_lds_dwordx4 v132, s[56:57]
	s_add_i32 m0, s58, 0x2000
	s_nop 0
	global_load_lds_dwordx4 v128, s[56:57]
	s_mov_b32 m0, s63
	s_nop 0
	global_load_lds_dwordx4 v134, s[100:101]
	s_mov_b32 m0, s64
	s_nop 0
	global_load_lds_dwordx4 v130, s[100:101]
	s_waitcnt vmcnt(8)
	s_waitcnt lgkmcnt(0)
	s_barrier
	s_setprio 1
	s_waitcnt lgkmcnt(0)
	v_mfma_f32_16x16x32_bf16 v[60:63], v[162:165], v[194:197], v[60:63]
	v_mfma_f32_16x16x32_bf16 v[56:59], v[170:173], v[194:197], v[56:59]
	v_mfma_f32_16x16x32_bf16 v[44:47], v[162:165], v[202:205], v[44:47]
	v_mfma_f32_16x16x32_bf16 v[40:43], v[170:173], v[202:205], v[40:43]
	v_mfma_f32_16x16x32_bf16 v[28:31], v[162:165], v[210:213], v[28:31]
	v_mfma_f32_16x16x32_bf16 v[24:27], v[170:173], v[210:213], v[24:27]
	v_mfma_f32_16x16x32_bf16 v[12:15], v[162:165], v[222:225], v[12:15]
	v_mfma_f32_16x16x32_bf16 v[8:11], v[170:173], v[222:225], v[8:11]
	v_mfma_f32_16x16x32_bf16 v[60:63], v[166:169], v[198:201], v[60:63]
	v_mfma_f32_16x16x32_bf16 v[56:59], v[174:177], v[198:201], v[56:59]
	v_mfma_f32_16x16x32_bf16 v[44:47], v[166:169], v[206:209], v[44:47]
	v_mfma_f32_16x16x32_bf16 v[40:43], v[174:177], v[206:209], v[40:43]
	v_mfma_f32_16x16x32_bf16 v[28:31], v[166:169], v[218:221], v[28:31]
	v_mfma_f32_16x16x32_bf16 v[24:27], v[174:177], v[218:221], v[24:27]
	v_mfma_f32_16x16x32_bf16 v[12:15], v[166:169], v[226:229], v[12:15]
	v_mfma_f32_16x16x32_bf16 v[8:11], v[174:177], v[226:229], v[8:11]
	s_setprio 0
	s_setprio 1
	v_mfma_f32_16x16x32_bf16 v[52:55], v[178:181], v[194:197], v[52:55]
	v_mfma_f32_16x16x32_bf16 v[48:51], v[186:189], v[194:197], v[48:51]
	v_mfma_f32_16x16x32_bf16 v[36:39], v[178:181], v[202:205], v[36:39]
	v_mfma_f32_16x16x32_bf16 v[32:35], v[186:189], v[202:205], v[32:35]
	v_mfma_f32_16x16x32_bf16 v[20:23], v[178:181], v[210:213], v[20:23]
	v_mfma_f32_16x16x32_bf16 v[16:19], v[186:189], v[210:213], v[16:19]
	v_mfma_f32_16x16x32_bf16 v[4:7], v[178:181], v[222:225], v[4:7]
	v_mfma_f32_16x16x32_bf16 v[0:3], v[186:189], v[222:225], v[0:3]
	v_mfma_f32_16x16x32_bf16 v[52:55], v[182:185], v[198:201], v[52:55]
	v_mfma_f32_16x16x32_bf16 v[48:51], v[190:193], v[198:201], v[48:51]
	v_mfma_f32_16x16x32_bf16 v[36:39], v[182:185], v[206:209], v[36:39]
	v_mfma_f32_16x16x32_bf16 v[32:35], v[190:193], v[206:209], v[32:35]
	v_mfma_f32_16x16x32_bf16 v[20:23], v[182:185], v[218:221], v[20:23]
	v_mfma_f32_16x16x32_bf16 v[16:19], v[190:193], v[218:221], v[16:19]
	v_mfma_f32_16x16x32_bf16 v[4:7], v[182:185], v[226:229], v[4:7]
	v_mfma_f32_16x16x32_bf16 v[0:3], v[190:193], v[226:229], v[0:3]
	s_setprio 0
	s_barrier
	s_add_i32 s75, s75, 2
	s_add_u32 s50, s50, 0x100
	s_addc_u32 s51, s51, 0
	s_add_u32 s73, s73, 0x100
	s_addc_u32 s74, s74, 0
	s_cmp_gt_u32 s75, 13
	s_cbranch_scc1 .LBB0_785
